# no cache invalidate at the barriers after P0, P2 and P5: every buffer the next phase loads is a first touch for that CU and XCD since their last invalidate (write-back at the barrier kept)
# speedup vs baseline: 1.0273x; 1.0063x over previous
.LBB0_193:
	s_or_b64 exec, exec, s[6:7]
	s_waitcnt vmcnt(0) lgkmcnt(0)
	s_nop 0
	s_waitcnt vmcnt(0)

.LBB0_209:
	s_or_b64 exec, exec, s[4:5]
	s_add_i32 s4, s24, 0x900
	s_mov_b32 s5, 0
	s_lshl_b64 s[4:5], s[4:5], 2
	s_add_u32 s4, s36, s4
	s_addc_u32 s5, s37, s5
	v_mov_b32_e32 v2, 1
	v_mov_b64_e32 v[0:1], s[4:5]
	s_waitcnt vmcnt(0) lgkmcnt(0)
	s_nop 0
	flat_atomic_add v[0:1], v2
	s_waitcnt vmcnt(0)

.LBB0_769:
	s_or_b64 exec, exec, s[14:15]
	s_waitcnt vmcnt(0) lgkmcnt(0)
	s_nop 0
	s_waitcnt vmcnt(0)

.LBB0_785:
	s_or_b64 exec, exec, s[14:15]
	s_add_i32 s82, s6, 0x900
	s_lshl_b64 s[6:7], s[82:83], 2
	s_add_u32 s6, s54, s6
	s_addc_u32 s7, s55, s7
	v_mov_b64_e32 v[0:1], s[6:7]
	s_waitcnt vmcnt(0) lgkmcnt(0)
	s_nop 0
	flat_atomic_add v[0:1], v228
	s_waitcnt vmcnt(0)

.LBB0_1250:
	s_or_b64 exec, exec, s[12:13]
	s_waitcnt vmcnt(0) lgkmcnt(0)
	s_nop 0
	s_waitcnt vmcnt(0)

.LBB0_1266:
	s_or_b64 exec, exec, s[10:11]
	s_add_i32 s82, s6, 0x900
	s_lshl_b64 s[6:7], s[82:83], 2
	s_add_u32 s6, s50, s6
	s_addc_u32 s7, s51, s7
	v_mov_b64_e32 v[0:1], s[6:7]
	s_waitcnt vmcnt(0) lgkmcnt(0)
	s_nop 0
	flat_atomic_add v[0:1], v228
	s_waitcnt vmcnt(0)
